# v55 + G1 rotary epilogue: the wait before the second column-half rotation only has to cover the cos/sin loads (older than the store just issued): vmcnt(0) -> vmcnt(1) at 8 sites
# speedup vs baseline: 1.0020x; 1.0020x over previous
.LBB0_366:
	v_readlane_b32 s8, v245, 21
	v_readlane_b32 s9, v245, 22
	v_lshl_or_b32 v122, s22, 8, v180
	v_ashrrev_i32_e32 v123, 31, v122
	v_mov_b64_e32 v[124:125], s[8:9]
	v_mad_i64_i32 v[124:125], s[8:9], v164, s33, v[124:125]
	v_lshl_add_u64 v[124:125], v[122:123], 1, v[124:125]
	v_cvt_pk_bf16_f32 v126, v126, v127
	v_cvt_pk_bf16_f32 v127, v168, v169
	v_mov_b32_e32 v182, v160
	v_mov_b32_e32 v183, v160
	v_cvt_pk_bf16_f32 v128, v128, v129
	v_cvt_pk_bf16_f32 v129, v166, v167
	global_store_dwordx4 v[124:125], v[126:129], off
	v_pk_mul_f32 v[118:119], v[182:183], v[118:119]
	s_and_b64 vcc, exec, s[36:37]
	v_mov_b32_e32 v126, v160
	v_mov_b32_e32 v127, v160
	v_pk_mul_f32 v[120:121], v[126:127], v[120:121]
	v_pk_mul_f32 v[116:117], v[126:127], v[116:117]
	v_pk_mul_f32 v[114:115], v[182:183], v[114:115]
	s_cbranch_vccnz .LBB0_368
	s_waitcnt vmcnt(1)
	v_pk_mul_f32 v[128:129], v[118:119], v[134:135] op_sel:[1,1] op_sel_hi:[0,1]
	v_pk_mul_f32 v[126:127], v[118:119], v[134:135]
	v_pk_fma_f32 v[118:119], v[118:119], v[134:135], v[128:129] op_sel_hi:[1,0,1]
	v_pk_mul_f32 v[166:167], v[114:115], v[130:131] op_sel:[1,1] op_sel_hi:[0,1]
	v_mul_f32_e32 v118, v121, v137
	v_pk_fma_f32 v[134:135], v[120:121], v[136:137], v[118:119] op_sel_hi:[1,1,0] neg_lo:[0,0,1] neg_hi:[0,0,1]
	v_mul_f32_e32 v118, v120, v137
	v_pk_fma_f32 v[136:137], v[120:121], v[136:137], v[118:119] op_sel:[1,0,0] op_sel_hi:[0,1,0]
	v_pk_mul_f32 v[120:121], v[114:115], v[130:131]
	v_pk_fma_f32 v[114:115], v[114:115], v[130:131], v[166:167] op_sel_hi:[1,0,1]
	v_sub_f32_e32 v118, v126, v128
	v_mul_f32_e32 v114, v117, v133
	v_pk_fma_f32 v[130:131], v[116:117], v[132:133], v[114:115] op_sel_hi:[1,1,0] neg_lo:[0,0,1] neg_hi:[0,0,1]
	v_mul_f32_e32 v114, v116, v133
	v_pk_fma_f32 v[132:133], v[116:117], v[132:133], v[114:115] op_sel:[1,0,0] op_sel_hi:[0,1,0]
	v_sub_f32_e32 v114, v120, v166
	v_mov_b32_e32 v120, v134
	v_mov_b32_e32 v121, v136
	v_mov_b32_e32 v116, v130
	v_mov_b32_e32 v117, v132

.LBB0_373:
	v_readlane_b32 s8, v245, 21
	v_readlane_b32 s9, v245, 22
	v_mov_b32_e32 v160, v161
	v_pk_mul_f32 v[102:103], v[160:161], v[102:103]
	v_mov_b64_e32 v[106:107], s[8:9]
	v_mad_i64_i32 v[106:107], s[8:9], v124, s33, v[106:107]
	v_cvt_pk_bf16_f32 v124, v110, v111
	v_cvt_pk_bf16_f32 v125, v126, v127
	v_cvt_pk_bf16_f32 v126, v108, v109
	v_mov_b32_e32 v108, v161
	v_mov_b32_e32 v109, v161
	v_lshl_add_u64 v[106:107], v[122:123], 1, v[106:107]
	v_pk_mul_f32 v[104:105], v[108:109], v[104:105]
	v_pk_mul_f32 v[100:101], v[108:109], v[100:101]
	s_and_b64 vcc, exec, s[36:37]
	v_pk_mul_f32 v[98:99], v[160:161], v[98:99]
	v_cvt_pk_bf16_f32 v127, v112, v113
	global_store_dwordx4 v[106:107], v[124:127], off
	s_cbranch_vccnz .LBB0_375
	s_waitcnt vmcnt(1)
	v_pk_mul_f32 v[110:111], v[102:103], v[118:119] op_sel:[1,1] op_sel_hi:[0,1]
	v_pk_mul_f32 v[108:109], v[102:103], v[118:119]
	v_pk_fma_f32 v[102:103], v[102:103], v[118:119], v[110:111] op_sel_hi:[1,0,1]
	s_nop 0
	v_mul_f32_e32 v102, v105, v121
	v_pk_fma_f32 v[112:113], v[104:105], v[120:121], v[102:103] op_sel_hi:[1,1,0] neg_lo:[0,0,1] neg_hi:[0,0,1]
	v_mul_f32_e32 v102, v104, v121
	v_pk_fma_f32 v[118:119], v[104:105], v[120:121], v[102:103] op_sel:[1,0,0] op_sel_hi:[0,1,0]
	v_pk_mul_f32 v[120:121], v[98:99], v[114:115] op_sel:[1,1] op_sel_hi:[0,1]
	v_pk_mul_f32 v[104:105], v[98:99], v[114:115]
	v_pk_fma_f32 v[98:99], v[98:99], v[114:115], v[120:121] op_sel_hi:[1,0,1]
	v_sub_f32_e32 v102, v108, v110
	v_mul_f32_e32 v98, v101, v117
	v_pk_fma_f32 v[114:115], v[100:101], v[116:117], v[98:99] op_sel_hi:[1,1,0] neg_lo:[0,0,1] neg_hi:[0,0,1]
	v_mul_f32_e32 v98, v100, v117
	v_pk_fma_f32 v[116:117], v[100:101], v[116:117], v[98:99] op_sel:[1,0,0] op_sel_hi:[0,1,0]
	v_sub_f32_e32 v98, v104, v120
	v_mov_b32_e32 v104, v112
	v_mov_b32_e32 v105, v118
	v_mov_b32_e32 v100, v114
	v_mov_b32_e32 v101, v116

.LBB0_380:
	v_readlane_b32 s8, v245, 21
	v_readlane_b32 s9, v245, 22
	v_mov_b32_e32 v159, v158
	v_pk_mul_f32 v[86:87], v[158:159], v[86:87]
	v_mov_b64_e32 v[90:91], s[8:9]
	v_mad_i64_i32 v[90:91], s[8:9], v106, s33, v[90:91]
	v_cvt_pk_bf16_f32 v106, v94, v95
	v_cvt_pk_bf16_f32 v107, v108, v109
	v_cvt_pk_bf16_f32 v108, v92, v93
	v_mov_b32_e32 v92, v158
	v_mov_b32_e32 v93, v158
	v_lshl_add_u64 v[90:91], v[122:123], 1, v[90:91]
	v_pk_mul_f32 v[88:89], v[92:93], v[88:89]
	v_pk_mul_f32 v[84:85], v[92:93], v[84:85]
	s_and_b64 vcc, exec, s[36:37]
	v_pk_mul_f32 v[82:83], v[158:159], v[82:83]
	v_cvt_pk_bf16_f32 v109, v96, v97
	global_store_dwordx4 v[90:91], v[106:109], off
	s_cbranch_vccnz .LBB0_382
	s_waitcnt vmcnt(1)
	v_pk_mul_f32 v[94:95], v[86:87], v[102:103] op_sel:[1,1] op_sel_hi:[0,1]
	v_pk_mul_f32 v[92:93], v[86:87], v[102:103]
	v_pk_fma_f32 v[86:87], v[86:87], v[102:103], v[94:95] op_sel_hi:[1,0,1]
	s_nop 0
	v_mul_f32_e32 v86, v89, v105
	v_pk_fma_f32 v[96:97], v[88:89], v[104:105], v[86:87] op_sel_hi:[1,1,0] neg_lo:[0,0,1] neg_hi:[0,0,1]
	v_mul_f32_e32 v86, v88, v105
	v_pk_fma_f32 v[102:103], v[88:89], v[104:105], v[86:87] op_sel:[1,0,0] op_sel_hi:[0,1,0]
	v_pk_mul_f32 v[104:105], v[82:83], v[98:99] op_sel:[1,1] op_sel_hi:[0,1]
	v_pk_mul_f32 v[88:89], v[82:83], v[98:99]
	v_pk_fma_f32 v[82:83], v[82:83], v[98:99], v[104:105] op_sel_hi:[1,0,1]
	v_sub_f32_e32 v86, v92, v94
	v_mul_f32_e32 v82, v85, v101
	v_pk_fma_f32 v[98:99], v[84:85], v[100:101], v[82:83] op_sel_hi:[1,1,0] neg_lo:[0,0,1] neg_hi:[0,0,1]
	v_mul_f32_e32 v82, v84, v101
	v_pk_fma_f32 v[100:101], v[84:85], v[100:101], v[82:83] op_sel:[1,0,0] op_sel_hi:[0,1,0]
	v_sub_f32_e32 v82, v88, v104
	v_mov_b32_e32 v88, v96
	v_mov_b32_e32 v89, v102
	v_mov_b32_e32 v84, v98
	v_mov_b32_e32 v85, v100

.LBB0_387:
	v_readlane_b32 s8, v245, 21
	v_readlane_b32 s9, v245, 22
	v_mov_b32_e32 v157, v156
	v_pk_mul_f32 v[70:71], v[156:157], v[70:71]
	v_mov_b64_e32 v[74:75], s[8:9]
	v_mad_i64_i32 v[74:75], s[8:9], v90, s33, v[74:75]
	v_cvt_pk_bf16_f32 v90, v78, v79
	v_cvt_pk_bf16_f32 v91, v92, v93
	v_cvt_pk_bf16_f32 v92, v76, v77
	v_mov_b32_e32 v76, v156
	v_mov_b32_e32 v77, v156
	v_lshl_add_u64 v[74:75], v[122:123], 1, v[74:75]
	v_pk_mul_f32 v[72:73], v[76:77], v[72:73]
	v_pk_mul_f32 v[68:69], v[76:77], v[68:69]
	s_and_b64 vcc, exec, s[36:37]
	v_pk_mul_f32 v[66:67], v[156:157], v[66:67]
	v_cvt_pk_bf16_f32 v93, v80, v81
	global_store_dwordx4 v[74:75], v[90:93], off
	s_cbranch_vccnz .LBB0_389
	s_waitcnt vmcnt(1)
	v_pk_mul_f32 v[78:79], v[70:71], v[86:87] op_sel:[1,1] op_sel_hi:[0,1]
	v_pk_mul_f32 v[76:77], v[70:71], v[86:87]
	v_pk_fma_f32 v[70:71], v[70:71], v[86:87], v[78:79] op_sel_hi:[1,0,1]
	s_nop 0
	v_mul_f32_e32 v70, v73, v89
	v_pk_fma_f32 v[80:81], v[72:73], v[88:89], v[70:71] op_sel_hi:[1,1,0] neg_lo:[0,0,1] neg_hi:[0,0,1]
	v_mul_f32_e32 v70, v72, v89
	v_pk_fma_f32 v[86:87], v[72:73], v[88:89], v[70:71] op_sel:[1,0,0] op_sel_hi:[0,1,0]
	v_pk_mul_f32 v[88:89], v[66:67], v[82:83] op_sel:[1,1] op_sel_hi:[0,1]
	v_pk_mul_f32 v[72:73], v[66:67], v[82:83]
	v_pk_fma_f32 v[66:67], v[66:67], v[82:83], v[88:89] op_sel_hi:[1,0,1]
	v_sub_f32_e32 v70, v76, v78
	v_mul_f32_e32 v66, v69, v85
	v_pk_fma_f32 v[82:83], v[68:69], v[84:85], v[66:67] op_sel_hi:[1,1,0] neg_lo:[0,0,1] neg_hi:[0,0,1]
	v_mul_f32_e32 v66, v68, v85
	v_pk_fma_f32 v[84:85], v[68:69], v[84:85], v[66:67] op_sel:[1,0,0] op_sel_hi:[0,1,0]
	v_sub_f32_e32 v66, v72, v88
	v_mov_b32_e32 v72, v80
	v_mov_b32_e32 v73, v86
	v_mov_b32_e32 v68, v82
	v_mov_b32_e32 v69, v84

.LBB0_394:
	v_readlane_b32 s8, v245, 21
	v_readlane_b32 s9, v245, 22
	v_mov_b32_e32 v155, v154
	v_pk_mul_f32 v[54:55], v[154:155], v[54:55]
	v_mov_b64_e32 v[58:59], s[8:9]
	v_mad_i64_i32 v[58:59], s[8:9], v74, s33, v[58:59]
	v_cvt_pk_bf16_f32 v74, v62, v63
	v_cvt_pk_bf16_f32 v75, v76, v77
	v_cvt_pk_bf16_f32 v76, v60, v61
	v_mov_b32_e32 v60, v154
	v_mov_b32_e32 v61, v154
	v_lshl_add_u64 v[58:59], v[122:123], 1, v[58:59]
	v_pk_mul_f32 v[56:57], v[60:61], v[56:57]
	v_pk_mul_f32 v[52:53], v[60:61], v[52:53]
	s_and_b64 vcc, exec, s[36:37]
	v_pk_mul_f32 v[50:51], v[154:155], v[50:51]
	v_cvt_pk_bf16_f32 v77, v64, v65
	global_store_dwordx4 v[58:59], v[74:77], off
	s_cbranch_vccnz .LBB0_396
	s_waitcnt vmcnt(1)
	v_pk_mul_f32 v[62:63], v[54:55], v[70:71] op_sel:[1,1] op_sel_hi:[0,1]
	v_pk_mul_f32 v[60:61], v[54:55], v[70:71]
	v_pk_fma_f32 v[54:55], v[54:55], v[70:71], v[62:63] op_sel_hi:[1,0,1]
	s_nop 0
	v_mul_f32_e32 v54, v57, v73
	v_pk_fma_f32 v[64:65], v[56:57], v[72:73], v[54:55] op_sel_hi:[1,1,0] neg_lo:[0,0,1] neg_hi:[0,0,1]
	v_mul_f32_e32 v54, v56, v73
	v_pk_fma_f32 v[70:71], v[56:57], v[72:73], v[54:55] op_sel:[1,0,0] op_sel_hi:[0,1,0]
	v_pk_mul_f32 v[72:73], v[50:51], v[66:67] op_sel:[1,1] op_sel_hi:[0,1]
	v_pk_mul_f32 v[56:57], v[50:51], v[66:67]
	v_pk_fma_f32 v[50:51], v[50:51], v[66:67], v[72:73] op_sel_hi:[1,0,1]
	v_sub_f32_e32 v54, v60, v62
	v_mul_f32_e32 v50, v53, v69
	v_pk_fma_f32 v[66:67], v[52:53], v[68:69], v[50:51] op_sel_hi:[1,1,0] neg_lo:[0,0,1] neg_hi:[0,0,1]
	v_mul_f32_e32 v50, v52, v69
	v_pk_fma_f32 v[68:69], v[52:53], v[68:69], v[50:51] op_sel:[1,0,0] op_sel_hi:[0,1,0]
	v_sub_f32_e32 v50, v56, v72
	v_mov_b32_e32 v56, v64
	v_mov_b32_e32 v57, v70
	v_mov_b32_e32 v52, v66
	v_mov_b32_e32 v53, v68

.LBB0_401:
	v_readlane_b32 s8, v245, 21
	v_readlane_b32 s9, v245, 22
	v_mov_b32_e32 v153, v152
	v_pk_mul_f32 v[38:39], v[152:153], v[38:39]
	v_mov_b64_e32 v[42:43], s[8:9]
	v_mad_i64_i32 v[42:43], s[8:9], v58, s33, v[42:43]
	v_cvt_pk_bf16_f32 v58, v46, v47
	v_cvt_pk_bf16_f32 v59, v60, v61
	v_cvt_pk_bf16_f32 v60, v44, v45
	v_mov_b32_e32 v44, v152
	v_mov_b32_e32 v45, v152
	v_lshl_add_u64 v[42:43], v[122:123], 1, v[42:43]
	v_pk_mul_f32 v[40:41], v[44:45], v[40:41]
	v_pk_mul_f32 v[36:37], v[44:45], v[36:37]
	s_and_b64 vcc, exec, s[36:37]
	v_pk_mul_f32 v[34:35], v[152:153], v[34:35]
	v_cvt_pk_bf16_f32 v61, v48, v49
	global_store_dwordx4 v[42:43], v[58:61], off
	s_cbranch_vccnz .LBB0_403
	s_waitcnt vmcnt(1)
	v_pk_mul_f32 v[46:47], v[38:39], v[54:55] op_sel:[1,1] op_sel_hi:[0,1]
	v_pk_mul_f32 v[44:45], v[38:39], v[54:55]
	v_pk_fma_f32 v[38:39], v[38:39], v[54:55], v[46:47] op_sel_hi:[1,0,1]
	s_nop 0
	v_mul_f32_e32 v38, v41, v57
	v_pk_fma_f32 v[48:49], v[40:41], v[56:57], v[38:39] op_sel_hi:[1,1,0] neg_lo:[0,0,1] neg_hi:[0,0,1]
	v_mul_f32_e32 v38, v40, v57
	v_pk_fma_f32 v[54:55], v[40:41], v[56:57], v[38:39] op_sel:[1,0,0] op_sel_hi:[0,1,0]
	v_pk_mul_f32 v[56:57], v[34:35], v[50:51] op_sel:[1,1] op_sel_hi:[0,1]
	v_pk_mul_f32 v[40:41], v[34:35], v[50:51]
	v_pk_fma_f32 v[34:35], v[34:35], v[50:51], v[56:57] op_sel_hi:[1,0,1]
	v_sub_f32_e32 v38, v44, v46
	v_mul_f32_e32 v34, v37, v53
	v_pk_fma_f32 v[50:51], v[36:37], v[52:53], v[34:35] op_sel_hi:[1,1,0] neg_lo:[0,0,1] neg_hi:[0,0,1]
	v_mul_f32_e32 v34, v36, v53
	v_pk_fma_f32 v[52:53], v[36:37], v[52:53], v[34:35] op_sel:[1,0,0] op_sel_hi:[0,1,0]
	v_sub_f32_e32 v34, v40, v56
	v_mov_b32_e32 v40, v48
	v_mov_b32_e32 v41, v54
	v_mov_b32_e32 v36, v50
	v_mov_b32_e32 v37, v52

.LBB0_408:
	v_readlane_b32 s8, v245, 21
	v_readlane_b32 s9, v245, 22
	v_mov_b32_e32 v46, v144
	v_mov_b32_e32 v47, v144
	v_mov_b64_e32 v[26:27], s[8:9]
	v_mad_i64_i32 v[26:27], s[8:9], v42, s33, v[26:27]
	v_cvt_pk_bf16_f32 v42, v30, v31
	v_cvt_pk_bf16_f32 v43, v44, v45
	v_cvt_pk_bf16_f32 v44, v28, v29
	v_mov_b32_e32 v28, v144
	v_mov_b32_e32 v29, v144
	v_lshl_add_u64 v[26:27], v[122:123], 1, v[26:27]
	v_pk_mul_f32 v[24:25], v[28:29], v[24:25]
	v_pk_mul_f32 v[22:23], v[46:47], v[22:23]
	v_pk_mul_f32 v[20:21], v[28:29], v[20:21]
	s_and_b64 vcc, exec, s[36:37]
	v_pk_mul_f32 v[18:19], v[46:47], v[18:19]
	v_cvt_pk_bf16_f32 v45, v32, v33
	global_store_dwordx4 v[26:27], v[42:45], off
	s_cbranch_vccnz .LBB0_410
	s_waitcnt vmcnt(1)
	v_pk_mul_f32 v[30:31], v[22:23], v[38:39] op_sel:[1,1] op_sel_hi:[0,1]
	v_pk_mul_f32 v[28:29], v[22:23], v[38:39]
	v_pk_fma_f32 v[22:23], v[22:23], v[38:39], v[30:31] op_sel_hi:[1,0,1]
	s_nop 0
	v_mul_f32_e32 v22, v25, v41
	v_pk_fma_f32 v[32:33], v[24:25], v[40:41], v[22:23] op_sel_hi:[1,1,0] neg_lo:[0,0,1] neg_hi:[0,0,1]
	v_mul_f32_e32 v22, v24, v41
	v_pk_fma_f32 v[38:39], v[24:25], v[40:41], v[22:23] op_sel:[1,0,0] op_sel_hi:[0,1,0]
	v_pk_mul_f32 v[40:41], v[18:19], v[34:35] op_sel:[1,1] op_sel_hi:[0,1]
	v_pk_mul_f32 v[24:25], v[18:19], v[34:35]
	v_pk_fma_f32 v[18:19], v[18:19], v[34:35], v[40:41] op_sel_hi:[1,0,1]
	v_sub_f32_e32 v22, v28, v30
	v_mul_f32_e32 v18, v21, v37
	v_pk_fma_f32 v[34:35], v[20:21], v[36:37], v[18:19] op_sel_hi:[1,1,0] neg_lo:[0,0,1] neg_hi:[0,0,1]
	v_mul_f32_e32 v18, v20, v37
	v_pk_fma_f32 v[36:37], v[20:21], v[36:37], v[18:19] op_sel:[1,0,0] op_sel_hi:[0,1,0]
	v_sub_f32_e32 v18, v24, v40
	v_mov_b32_e32 v24, v32
	v_mov_b32_e32 v25, v38
	v_mov_b32_e32 v20, v34
	v_mov_b32_e32 v21, v36

.LBB0_415:
	v_readlane_b32 s8, v245, 21
	v_readlane_b32 s9, v245, 22
	v_mov_b32_e32 v30, v145
	v_mov_b32_e32 v31, v145
	v_mov_b64_e32 v[10:11], s[8:9]
	v_mad_i64_i32 v[10:11], s[8:9], v26, s33, v[10:11]
	v_mov_b32_e32 v144, v145
	v_lshl_add_u64 v[10:11], v[122:123], 1, v[10:11]
	v_pk_mul_f32 v[8:9], v[144:145], v[8:9]
	v_pk_mul_f32 v[6:7], v[30:31], v[6:7]
	v_pk_mul_f32 v[4:5], v[144:145], v[4:5]
	s_and_b64 vcc, exec, s[36:37]
	v_pk_mul_f32 v[2:3], v[30:31], v[2:3]
	v_cvt_pk_bf16_f32 v26, v14, v15
	v_cvt_pk_bf16_f32 v27, v28, v29
	v_cvt_pk_bf16_f32 v28, v12, v13
	v_cvt_pk_bf16_f32 v29, v16, v17
	global_store_dwordx4 v[10:11], v[26:29], off
	s_cbranch_vccnz .LBB0_417
	s_waitcnt vmcnt(1)
	v_pk_mul_f32 v[14:15], v[6:7], v[22:23] op_sel:[1,1] op_sel_hi:[0,1]
	v_pk_mul_f32 v[12:13], v[6:7], v[22:23]
	v_pk_fma_f32 v[6:7], v[6:7], v[22:23], v[14:15] op_sel_hi:[1,0,1]
	s_nop 0
	v_mul_f32_e32 v6, v9, v25
	v_pk_fma_f32 v[16:17], v[8:9], v[24:25], v[6:7] op_sel_hi:[1,1,0] neg_lo:[0,0,1] neg_hi:[0,0,1]
	v_mul_f32_e32 v6, v8, v25
	v_pk_fma_f32 v[22:23], v[8:9], v[24:25], v[6:7] op_sel:[1,0,0] op_sel_hi:[0,1,0]
	v_pk_mul_f32 v[24:25], v[2:3], v[18:19] op_sel:[1,1] op_sel_hi:[0,1]
	v_pk_mul_f32 v[8:9], v[2:3], v[18:19]
	v_pk_fma_f32 v[2:3], v[2:3], v[18:19], v[24:25] op_sel_hi:[1,0,1]
	v_sub_f32_e32 v6, v12, v14
	v_mul_f32_e32 v2, v5, v21
	v_pk_fma_f32 v[18:19], v[4:5], v[20:21], v[2:3] op_sel_hi:[1,1,0] neg_lo:[0,0,1] neg_hi:[0,0,1]
	v_mul_f32_e32 v2, v4, v21
	v_pk_fma_f32 v[20:21], v[4:5], v[20:21], v[2:3] op_sel:[1,0,0] op_sel_hi:[0,1,0]
	v_sub_f32_e32 v2, v8, v24
	v_mov_b32_e32 v8, v16
	v_mov_b32_e32 v9, v22
	v_mov_b32_e32 v4, v18
	v_mov_b32_e32 v5, v20
